# E3 queue: first item per workgroup fixed so items sharing prefix states or K/V start 8 workgroups apart (same XCD under round-robin placement)
# speedup vs baseline: 1.0102x; 1.0015x over previous
.LBB0_564:
	s_andn2_b64 vcc, exec, s[12:13]
	s_cbranch_vccnz .LBB0_773
	s_add_u32 s12, s80, 0xe618000
	s_addc_u32 s13, s81, 0
	s_add_u32 s0, s80, 0xef98000
	s_addc_u32 s1, s81, 0
	s_add_u32 s16, s80, 0xec18000
	v_writelane_b32 v254, s0, 51
	s_addc_u32 s17, s81, 0
	s_nop 0
	v_writelane_b32 v254, s1, 52
	s_add_u32 s0, s80, 0xcde8000
	s_addc_u32 s1, s81, 0
	v_writelane_b32 v254, s0, 49
	s_nop 1
	v_writelane_b32 v254, s1, 50
	s_add_u32 s0, s80, 0xe5e8000
	s_addc_u32 s1, s81, 0
	v_writelane_b32 v254, s0, 53
	s_lshl_b64 s[22:23], s[58:59], 14
	s_cmp_gt_i32 s73, 3
	v_writelane_b32 v254, s1, 54
	s_mov_b64 s[0:1], -1
	s_cbranch_scc0 .LBB0_656
	v_readlane_b32 s0, v254, 39
	v_readlane_b32 s1, v254, 40
	s_lshl_b64 s[0:1], s[0:1], 2
	s_add_u32 s0, s80, s0
	s_addc_u32 s1, s81, s1
	s_add_u32 s0, s0, 0x12cd8044
	s_addc_u32 s1, s1, 0
	v_writelane_b32 v254, s0, 59
	s_nop 1
	v_writelane_b32 v254, s1, 60
	s_sub_i32 s0, s58, 32
	v_writelane_b32 v254, s0, 61
	v_readlane_b32 s3, v252, 0
	s_nop 3
	s_and_b32 s96, s3, 7
	s_lshl_b32 s96, s96, 4
	s_bfe_u32 s97, s3, 0x40003
	s_add_i32 s96, s96, s97
	s_lshr_b32 s97, s3, 7
	s_lshl_b32 s97, s97, 7
	s_add_i32 s3, s96, s97
	s_and_saveexec_b64 s[0:1], s[92:93]
	v_mov_b32_e32 v2, s69
	v_mov_b32_e32 v0, s3
	ds_write_b32 v2, v0
	s_branch .LBB0_574

.LBB0_573:
	s_or_b64 exec, exec, s[14:15]
	s_waitcnt vmcnt(0)
	v_readfirstlane_b32 s3, v2
	s_addk_i32 s3, 0x100
	v_mov_b32_e32 v2, s69
	s_nop 0
	v_add_u32_e32 v0, s3, v0
	ds_write_b32 v2, v0
